# GEMM tile prologues: 128 v_mov accumulator zeroing replaced by 8 zero-operand MFMAs with inline-zero C
# baseline (speedup 1.0000x reference)
; #define H_LOAD(KT) do { _Pragma("unroll") for (int i = 0; i < 4; ++i) { ra[i] = *(const u32x4*)(Ap + (size_t)i * 64 * K + (KT) * 64); rb[i] = *(const u32x4*)(Bp + (size_t)i * 64 * K + (KT) * 64); } } while (0)
; #define H_STORE(BUF) do { unsigned char* Aw = As0 + (BUF) * OPB; unsigned char* Bw = Bs0 + (BUF) * OPB; \
;       _Pragma("unroll") for (int i = 0; i < 4; ++i) { *(u32x4*)(Aw + (ldrow + 64 * i) * LDS_STRIDE + ldcol * 2) = ra[i]; *(u32x4*)(Bw + (ldrow + 64 * i) * LDS_STRIDE + ldcol * 2) = rb[i]; } } while (0)
; template <class Epi>
; DI void gemm_phase512(const bf16_t* A, const bf16_t* Bt, int mtiles, int ntiles, int K, int Kper, int ksplit, const Epi& epi,
;                       unsigned char* smem, int bid, int nb) {
;     ...
;     f32x16 acc[2][4];
; #pragma unroll
;     for (int a = 0; a < 2; ++a)
; #pragma unroll
;       for (int b = 0; b < 4; ++b)
; #pragma unroll
;         for (int i = 0; i < 16; ++i) acc[a][b][i] = 0.f;
;     H_STORE(0);
;     H_LOAD(1);
;     __syncthreads();
.LBB0_127:
	v_add_co_u32_e32 v0, vcc, s35, v160
	s_waitcnt vmcnt(7)
	ds_write_b128 v168, v[128:131]
	s_waitcnt vmcnt(1)
	ds_write_b128 v169, v[156:159]
	ds_write_b128 v168, v[132:135] offset:9216
	ds_write_b128 v169, v[136:139] offset:9216
	ds_write_b128 v168, v[140:143] offset:18432
	ds_write_b128 v169, v[144:147] offset:18432
	ds_write_b128 v168, v[148:151] offset:27648
	s_waitcnt vmcnt(0)
	ds_write_b128 v169, v[152:155] offset:27648
	v_addc_co_u32_e32 v1, vcc, 0, v161, vcc
	global_load_dwordx4 v[128:131], v[160:161], off offset:128
	global_load_dwordx4 v[132:135], v[0:1], off offset:128
	v_add_co_u32_e32 v0, vcc, s35, v170
	s_mov_b32 s26, 0
	s_nop 0
	v_addc_co_u32_e32 v1, vcc, 0, v171, vcc
	global_load_dwordx4 v[136:139], v[0:1], off offset:128
	v_add_co_u32_e32 v0, vcc, s36, v160
	s_movk_i32 s27, 0x80
	s_nop 0
	v_addc_co_u32_e32 v1, vcc, 0, v161, vcc
	global_load_dwordx4 v[140:143], v[0:1], off offset:128
	v_add_co_u32_e32 v0, vcc, s36, v170
	s_nop 1
	v_addc_co_u32_e32 v1, vcc, 0, v171, vcc
	global_load_dwordx4 v[144:147], v[0:1], off offset:128
	v_add_co_u32_e32 v0, vcc, 0x60000, v160
	s_nop 1
	v_addc_co_u32_e32 v1, vcc, 0, v161, vcc
	global_load_dwordx4 v[152:155], v[0:1], off offset:128
	v_add_co_u32_e32 v0, vcc, 0x60000, v170
	s_nop 1
	v_addc_co_u32_e32 v1, vcc, 0, v171, vcc
	global_load_dwordx4 v[148:151], v[170:171], off offset:128
	global_load_dwordx4 v[156:159], v[0:1], off offset:128
	v_mov_b32_e32 v200, 0
	v_mov_b32_e32 v201, 0
	v_mov_b32_e32 v202, 0
	v_mov_b32_e32 v203, 0
	s_nop 1
	v_mfma_f32_32x32x16_bf16 v[0:15], v[200:203], v[200:203], 0
	v_mfma_f32_32x32x16_bf16 v[16:31], v[200:203], v[200:203], 0
	v_mfma_f32_32x32x16_bf16 v[32:47], v[200:203], v[200:203], 0
	v_mfma_f32_32x32x16_bf16 v[48:63], v[200:203], v[200:203], 0
	v_mfma_f32_32x32x16_bf16 v[64:79], v[200:203], v[200:203], 0
	v_mfma_f32_32x32x16_bf16 v[80:95], v[200:203], v[200:203], 0
	v_mfma_f32_32x32x16_bf16 v[96:111], v[200:203], v[200:203], 0
	v_mfma_f32_32x32x16_bf16 v[112:127], v[200:203], v[200:203], 0
	s_waitcnt lgkmcnt(0)
	s_barrier
	ds_read_b128 v[200:203], v191
	ds_read_b128 v[224:227], v191 offset:4608
	ds_read_b128 v[204:207], v192
	ds_read_b128 v[208:211], v192 offset:4608
	ds_read_b128 v[238:241], v192 offset:9216
	ds_read_b128 v[242:245], v192 offset:13824

; #define H_LOAD(KT) do { _Pragma("unroll") for (int i = 0; i < 4; ++i) { ra[i] = *(const u32x4*)(Ap + (size_t)i * 64 * K + (KT) * 64); rb[i] = *(const u32x4*)(Bp + (size_t)i * 64 * K + (KT) * 64); } } while (0)
; #define H_STORE(BUF) do { unsigned char* Aw = As0 + (BUF) * OPB; unsigned char* Bw = Bs0 + (BUF) * OPB; \
;       _Pragma("unroll") for (int i = 0; i < 4; ++i) { *(u32x4*)(Aw + (ldrow + 64 * i) * LDS_STRIDE + ldcol * 2) = ra[i]; *(u32x4*)(Bw + (ldrow + 64 * i) * LDS_STRIDE + ldcol * 2) = rb[i]; } } while (0)
; template <class Epi>
; DI void gemm_phase512(const bf16_t* A, const bf16_t* Bt, int mtiles, int ntiles, int K, int Kper, int ksplit, const Epi& epi,
;                       unsigned char* smem, int bid, int nb) {
;     ...
;     f32x16 acc[2][4];
; #pragma unroll
;     for (int a = 0; a < 2; ++a)
; #pragma unroll
;       for (int b = 0; b < 4; ++b)
; #pragma unroll
;         for (int i = 0; i < 16; ++i) acc[a][b][i] = 0.f;
;     H_STORE(0);
;     H_LOAD(1);
;     __syncthreads();
.LBB0_582:
	v_add_co_u32_e32 v0, vcc, s35, v166
	s_waitcnt vmcnt(7)
	ds_write_b128 v164, v[128:131]
	s_waitcnt vmcnt(1)
	ds_write_b128 v165, v[156:159]
	ds_write_b128 v164, v[132:135] offset:9216
	ds_write_b128 v165, v[136:139] offset:9216
	ds_write_b128 v164, v[140:143] offset:18432
	ds_write_b128 v165, v[144:147] offset:18432
	ds_write_b128 v164, v[148:151] offset:27648
	s_waitcnt vmcnt(0)
	ds_write_b128 v165, v[152:155] offset:27648
	v_addc_co_u32_e32 v1, vcc, 0, v167, vcc
	global_load_dwordx4 v[128:131], v[166:167], off offset:128
	global_load_dwordx4 v[132:135], v[0:1], off offset:128
	v_add_co_u32_e32 v0, vcc, s35, v168
	s_mov_b32 s27, 0
	s_nop 0
	v_addc_co_u32_e32 v1, vcc, 0, v169, vcc
	global_load_dwordx4 v[136:139], v[0:1], off offset:128
	v_add_co_u32_e32 v0, vcc, s36, v166
	s_movk_i32 s30, 0x80
	s_nop 0
	v_addc_co_u32_e32 v1, vcc, 0, v167, vcc
	global_load_dwordx4 v[140:143], v[0:1], off offset:128
	v_add_co_u32_e32 v0, vcc, s36, v168
	s_nop 1
	v_addc_co_u32_e32 v1, vcc, 0, v169, vcc
	global_load_dwordx4 v[144:147], v[0:1], off offset:128
	v_add_co_u32_e32 v0, vcc, 0x60000, v166
	s_nop 1
	v_addc_co_u32_e32 v1, vcc, 0, v167, vcc
	global_load_dwordx4 v[152:155], v[0:1], off offset:128
	v_add_co_u32_e32 v0, vcc, 0x60000, v168
	s_nop 1
	v_addc_co_u32_e32 v1, vcc, 0, v169, vcc
	global_load_dwordx4 v[148:151], v[168:169], off offset:128
	global_load_dwordx4 v[156:159], v[0:1], off offset:128
	v_mov_b32_e32 v198, 0
	v_mov_b32_e32 v199, 0
	v_mov_b32_e32 v200, 0
	v_mov_b32_e32 v201, 0
	s_nop 1
	v_mfma_f32_32x32x16_bf16 v[0:15], v[198:201], v[198:201], 0
	v_mfma_f32_32x32x16_bf16 v[16:31], v[198:201], v[198:201], 0
	v_mfma_f32_32x32x16_bf16 v[32:47], v[198:201], v[198:201], 0
	v_mfma_f32_32x32x16_bf16 v[48:63], v[198:201], v[198:201], 0
	v_mfma_f32_32x32x16_bf16 v[64:79], v[198:201], v[198:201], 0
	v_mfma_f32_32x32x16_bf16 v[80:95], v[198:201], v[198:201], 0
	v_mfma_f32_32x32x16_bf16 v[96:111], v[198:201], v[198:201], 0
	v_mfma_f32_32x32x16_bf16 v[112:127], v[198:201], v[198:201], 0
	s_waitcnt lgkmcnt(0)
	s_barrier
	ds_read_b128 v[198:201], v189
	ds_read_b128 v[224:227], v189 offset:4608
	ds_read_b128 v[202:205], v190
	ds_read_b128 v[206:209], v190 offset:4608
	ds_read_b128 v[238:241], v190 offset:9216
	ds_read_b128 v[242:245], v190 offset:13824

; #define H_LOAD(KT) do { _Pragma("unroll") for (int i = 0; i < 4; ++i) { ra[i] = *(const u32x4*)(Ap + (size_t)i * 64 * K + (KT) * 64); rb[i] = *(const u32x4*)(Bp + (size_t)i * 64 * K + (KT) * 64); } } while (0)
; #define H_STORE(BUF) do { unsigned char* Aw = As0 + (BUF) * OPB; unsigned char* Bw = Bs0 + (BUF) * OPB; \
;       _Pragma("unroll") for (int i = 0; i < 4; ++i) { *(u32x4*)(Aw + (ldrow + 64 * i) * LDS_STRIDE + ldcol * 2) = ra[i]; *(u32x4*)(Bw + (ldrow + 64 * i) * LDS_STRIDE + ldcol * 2) = rb[i]; } } while (0)
; template <class Epi>
; DI void gemm_phase512(const bf16_t* A, const bf16_t* Bt, int mtiles, int ntiles, int K, int Kper, int ksplit, const Epi& epi,
;                       unsigned char* smem, int bid, int nb) {
;     ...
;     f32x16 acc[2][4];
; #pragma unroll
;     for (int a = 0; a < 2; ++a)
; #pragma unroll
;       for (int b = 0; b < 4; ++b)
; #pragma unroll
;         for (int i = 0; i < 16; ++i) acc[a][b][i] = 0.f;
;     H_STORE(0);
;     H_LOAD(1);
;     __syncthreads();
.LBB0_703:
	v_add_co_u32_e32 v0, vcc, s35, v164
	s_waitcnt vmcnt(7)
	ds_write_b128 v168, v[128:131]
	s_waitcnt vmcnt(1)
	ds_write_b128 v169, v[156:159]
	ds_write_b128 v168, v[132:135] offset:9216
	ds_write_b128 v169, v[136:139] offset:9216
	ds_write_b128 v168, v[140:143] offset:18432
	ds_write_b128 v169, v[144:147] offset:18432
	ds_write_b128 v168, v[148:151] offset:27648
	s_waitcnt vmcnt(0)
	ds_write_b128 v169, v[152:155] offset:27648
	v_addc_co_u32_e32 v1, vcc, 0, v165, vcc
	global_load_dwordx4 v[128:131], v[164:165], off offset:128
	global_load_dwordx4 v[132:135], v[0:1], off offset:128
	v_add_co_u32_e32 v0, vcc, s35, v170
	s_mov_b32 s27, 0
	s_nop 0
	v_addc_co_u32_e32 v1, vcc, 0, v171, vcc
	global_load_dwordx4 v[136:139], v[0:1], off offset:128
	v_add_co_u32_e32 v0, vcc, s36, v164
	s_movk_i32 s28, 0x80
	s_nop 0
	v_addc_co_u32_e32 v1, vcc, 0, v165, vcc
	global_load_dwordx4 v[140:143], v[0:1], off offset:128
	v_add_co_u32_e32 v0, vcc, s36, v170
	s_nop 1
	v_addc_co_u32_e32 v1, vcc, 0, v171, vcc
	global_load_dwordx4 v[144:147], v[0:1], off offset:128
	v_add_co_u32_e32 v0, vcc, 0x60000, v164
	s_nop 1
	v_addc_co_u32_e32 v1, vcc, 0, v165, vcc
	global_load_dwordx4 v[152:155], v[0:1], off offset:128
	v_add_co_u32_e32 v0, vcc, 0x60000, v170
	s_nop 1
	v_addc_co_u32_e32 v1, vcc, 0, v171, vcc
	global_load_dwordx4 v[148:151], v[170:171], off offset:128
	global_load_dwordx4 v[156:159], v[0:1], off offset:128
	v_mov_b32_e32 v200, 0
	v_mov_b32_e32 v201, 0
	v_mov_b32_e32 v202, 0
	v_mov_b32_e32 v203, 0
	s_nop 1
	v_mfma_f32_32x32x16_bf16 v[0:15], v[200:203], v[200:203], 0
	v_mfma_f32_32x32x16_bf16 v[16:31], v[200:203], v[200:203], 0
	v_mfma_f32_32x32x16_bf16 v[32:47], v[200:203], v[200:203], 0
	v_mfma_f32_32x32x16_bf16 v[48:63], v[200:203], v[200:203], 0
	v_mfma_f32_32x32x16_bf16 v[64:79], v[200:203], v[200:203], 0
	v_mfma_f32_32x32x16_bf16 v[80:95], v[200:203], v[200:203], 0
	v_mfma_f32_32x32x16_bf16 v[96:111], v[200:203], v[200:203], 0
	v_mfma_f32_32x32x16_bf16 v[112:127], v[200:203], v[200:203], 0
	s_waitcnt lgkmcnt(0)
	s_barrier
	ds_read_b128 v[200:203], v191
	ds_read_b128 v[224:227], v191 offset:4608
	ds_read_b128 v[204:207], v192
	ds_read_b128 v[208:211], v192 offset:4608
	ds_read_b128 v[238:241], v192 offset:9216
	ds_read_b128 v[242:245], v192 offset:13824

; #define H_LOAD(KT) do { _Pragma("unroll") for (int i = 0; i < 4; ++i) { ra[i] = *(const u32x4*)(Ap + (size_t)i * 64 * K + (KT) * 64); rb[i] = *(const u32x4*)(Bp + (size_t)i * 64 * K + (KT) * 64); } } while (0)
; #define H_STORE(BUF) do { unsigned char* Aw = As0 + (BUF) * OPB; unsigned char* Bw = Bs0 + (BUF) * OPB; \
;       _Pragma("unroll") for (int i = 0; i < 4; ++i) { *(u32x4*)(Aw + (ldrow + 64 * i) * LDS_STRIDE + ldcol * 2) = ra[i]; *(u32x4*)(Bw + (ldrow + 64 * i) * LDS_STRIDE + ldcol * 2) = rb[i]; } } while (0)
; template <class Epi>
; DI void gemm_phase512(const bf16_t* A, const bf16_t* Bt, int mtiles, int ntiles, int K, int Kper, int ksplit, const Epi& epi,
;                       unsigned char* smem, int bid, int nb) {
;     ...
;     f32x16 acc[2][4];
; #pragma unroll
;     for (int a = 0; a < 2; ++a)
; #pragma unroll
;       for (int b = 0; b < 4; ++b)
; #pragma unroll
;         for (int i = 0; i < 16; ++i) acc[a][b][i] = 0.f;
;     H_STORE(0);
;     H_LOAD(1);
;     __syncthreads();
.LBB0_763:
	v_add_co_u32_e32 v0, vcc, s97, v162
	s_waitcnt vmcnt(7)
	ds_write_b128 v160, v[128:131]
	s_waitcnt vmcnt(1)
	ds_write_b128 v161, v[156:159]
	ds_write_b128 v160, v[132:135] offset:9216
	ds_write_b128 v161, v[136:139] offset:9216
	ds_write_b128 v160, v[140:143] offset:18432
	ds_write_b128 v161, v[144:147] offset:18432
	ds_write_b128 v160, v[148:151] offset:27648
	s_waitcnt vmcnt(0)
	ds_write_b128 v161, v[152:155] offset:27648
	v_addc_co_u32_e32 v1, vcc, 0, v163, vcc
	global_load_dwordx4 v[128:131], v[162:163], off offset:128
	global_load_dwordx4 v[132:135], v[0:1], off offset:128
	v_add_co_u32_e32 v0, vcc, s97, v164
	s_mov_b32 s2, 0
	s_nop 0
	v_addc_co_u32_e32 v1, vcc, 0, v165, vcc
	global_load_dwordx4 v[140:143], v[0:1], off offset:128
	v_add_co_u32_e32 v0, vcc, s33, v162
	s_movk_i32 s3, 0x80
	s_nop 0
	v_addc_co_u32_e32 v1, vcc, 0, v163, vcc
	global_load_dwordx4 v[136:139], v[0:1], off offset:128
	v_add_co_u32_e32 v0, vcc, s33, v164
	s_nop 1
	v_addc_co_u32_e32 v1, vcc, 0, v165, vcc
	global_load_dwordx4 v[148:151], v[0:1], off offset:128
	v_add_co_u32_e32 v0, vcc, 0x180000, v162
	s_nop 1
	v_addc_co_u32_e32 v1, vcc, 0, v163, vcc
	global_load_dwordx4 v[144:147], v[0:1], off offset:128
	v_add_co_u32_e32 v0, vcc, 0x180000, v164
	s_nop 1
	v_addc_co_u32_e32 v1, vcc, 0, v165, vcc
	global_load_dwordx4 v[152:155], v[164:165], off offset:128
	global_load_dwordx4 v[156:159], v[0:1], off offset:128
	v_mov_b32_e32 v198, 0
	v_mov_b32_e32 v199, 0
	v_mov_b32_e32 v200, 0
	v_mov_b32_e32 v201, 0
	s_nop 1
	v_mfma_f32_32x32x16_bf16 v[0:15], v[198:201], v[198:201], 0
	v_mfma_f32_32x32x16_bf16 v[16:31], v[198:201], v[198:201], 0
	v_mfma_f32_32x32x16_bf16 v[32:47], v[198:201], v[198:201], 0
	v_mfma_f32_32x32x16_bf16 v[48:63], v[198:201], v[198:201], 0
	v_mfma_f32_32x32x16_bf16 v[64:79], v[198:201], v[198:201], 0
	v_mfma_f32_32x32x16_bf16 v[80:95], v[198:201], v[198:201], 0
	v_mfma_f32_32x32x16_bf16 v[96:111], v[198:201], v[198:201], 0
	v_mfma_f32_32x32x16_bf16 v[112:127], v[198:201], v[198:201], 0
	s_waitcnt lgkmcnt(0)
	s_barrier
	ds_read_b128 v[198:201], v185
	ds_read_b128 v[224:227], v185 offset:4608
	ds_read_b128 v[202:205], v186
	ds_read_b128 v[206:209], v186 offset:4608
	ds_read_b128 v[238:241], v186 offset:9216
	ds_read_b128 v[242:245], v186 offset:13824

; #define H_LOAD(KT) do { _Pragma("unroll") for (int i = 0; i < 4; ++i) { ra[i] = *(const u32x4*)(Ap + (size_t)i * 64 * K + (KT) * 64); rb[i] = *(const u32x4*)(Bp + (size_t)i * 64 * K + (KT) * 64); } } while (0)
; #define H_STORE(BUF) do { unsigned char* Aw = As0 + (BUF) * OPB; unsigned char* Bw = Bs0 + (BUF) * OPB; \
;       _Pragma("unroll") for (int i = 0; i < 4; ++i) { *(u32x4*)(Aw + (ldrow + 64 * i) * LDS_STRIDE + ldcol * 2) = ra[i]; *(u32x4*)(Bw + (ldrow + 64 * i) * LDS_STRIDE + ldcol * 2) = rb[i]; } } while (0)
; template <class Epi>
; DI void gemm_phase512(const bf16_t* A, const bf16_t* Bt, int mtiles, int ntiles, int K, int Kper, int ksplit, const Epi& epi,
;                       unsigned char* smem, int bid, int nb) {
;     ...
;     f32x16 acc[2][4];
; #pragma unroll
;     for (int a = 0; a < 2; ++a)
; #pragma unroll
;       for (int b = 0; b < 4; ++b)
; #pragma unroll
;         for (int i = 0; i < 16; ++i) acc[a][b][i] = 0.f;
;     H_STORE(0);
;     H_LOAD(1);
;     __syncthreads();
.LBB0_772:
	v_add_co_u32_e32 v0, vcc, s97, v164
	s_waitcnt vmcnt(7)
	ds_write_b128 v166, v[128:131]
	s_waitcnt vmcnt(1)
	ds_write_b128 v167, v[156:159]
	ds_write_b128 v166, v[132:135] offset:9216
	ds_write_b128 v167, v[136:139] offset:9216
	ds_write_b128 v166, v[140:143] offset:18432
	ds_write_b128 v167, v[144:147] offset:18432
	ds_write_b128 v166, v[148:151] offset:27648
	s_waitcnt vmcnt(0)
	ds_write_b128 v167, v[152:155] offset:27648
	v_addc_co_u32_e32 v1, vcc, 0, v165, vcc
	global_load_dwordx4 v[128:131], v[164:165], off offset:128
	global_load_dwordx4 v[132:135], v[0:1], off offset:128
	v_add_co_u32_e32 v0, vcc, s97, v168
	s_mov_b32 s24, 0
	s_nop 0
	v_addc_co_u32_e32 v1, vcc, 0, v169, vcc
	global_load_dwordx4 v[136:139], v[0:1], off offset:128
	v_add_co_u32_e32 v0, vcc, s33, v164
	s_movk_i32 s27, 0x80
	s_nop 0
	v_addc_co_u32_e32 v1, vcc, 0, v165, vcc
	global_load_dwordx4 v[140:143], v[0:1], off offset:128
	v_add_co_u32_e32 v0, vcc, s33, v168
	s_nop 1
	v_addc_co_u32_e32 v1, vcc, 0, v169, vcc
	global_load_dwordx4 v[144:147], v[0:1], off offset:128
	v_add_co_u32_e32 v0, vcc, 0x180000, v164
	s_nop 1
	v_addc_co_u32_e32 v1, vcc, 0, v165, vcc
	global_load_dwordx4 v[152:155], v[0:1], off offset:128
	v_add_co_u32_e32 v0, vcc, 0x180000, v168
	s_nop 1
	v_addc_co_u32_e32 v1, vcc, 0, v169, vcc
	global_load_dwordx4 v[148:151], v[168:169], off offset:128
	global_load_dwordx4 v[156:159], v[0:1], off offset:128
	v_mov_b32_e32 v198, 0
	v_mov_b32_e32 v199, 0
	v_mov_b32_e32 v200, 0
	v_mov_b32_e32 v201, 0
	s_nop 1
	v_mfma_f32_32x32x16_bf16 v[0:15], v[198:201], v[198:201], 0
	v_mfma_f32_32x32x16_bf16 v[16:31], v[198:201], v[198:201], 0
	v_mfma_f32_32x32x16_bf16 v[32:47], v[198:201], v[198:201], 0
	v_mfma_f32_32x32x16_bf16 v[48:63], v[198:201], v[198:201], 0
	v_mfma_f32_32x32x16_bf16 v[64:79], v[198:201], v[198:201], 0
	v_mfma_f32_32x32x16_bf16 v[80:95], v[198:201], v[198:201], 0
	v_mfma_f32_32x32x16_bf16 v[96:111], v[198:201], v[198:201], 0
	v_mfma_f32_32x32x16_bf16 v[112:127], v[198:201], v[198:201], 0
	s_waitcnt lgkmcnt(0)
	s_barrier
	ds_read_b128 v[198:201], v189
	ds_read_b128 v[224:227], v189 offset:4608
	ds_read_b128 v[202:205], v190
	ds_read_b128 v[206:209], v190 offset:4608
	ds_read_b128 v[238:241], v190 offset:9216
	ds_read_b128 v[242:245], v190 offset:13824
